# P4 row-panel exchange: partial sums published with write-through (sc0 sc1) stores + vmcnt(0) instead of an L2 write-back fence before the arrival counter
# speedup vs baseline: 1.0093x; 1.0015x over previous
; DI float xor32_sum(float x) { auto r = __builtin_amdgcn_permlane32_swap(__float_as_uint(x), __float_as_uint(x), false, false); return __uint_as_float(r[0]) + __uint_as_float(r[1]); }
; DI float xor16_sum(float x) { auto r = __builtin_amdgcn_permlane16_swap(__float_as_uint(x), __float_as_uint(x), false, false); return __uint_as_float(r[0]) + __uint_as_float(r[1]); }
;     DI void fused(pg8::f32x4 (&acc)[2][2][4][2], const pg8::Unit& u, int wr, int wc, int fr, int fq, PG8_LAS unsigned char* lds, int wid, int lane) const {
;     ...
; #pragma unroll
;         for (int ai = 0; ai < 2; ++ai)
; #pragma unroll
;             for (int m = 0; m < 4; ++m) {
;                 const size_t tok = (size_t)u.pm * 256 + ai * 128 + wr * 64 + m * 16 + fr;
;                 float ss = 0.f;
; #pragma unroll
;                 for (int bj = 0; bj < 2; ++bj)
; #pragma unroll
;                     for (int n = 0; n < 2; ++n) {
;                         const size_t off = tok * 1024 + u.pn * 256 + bj * 128 + wc * 32 + n * 16 + 4 * fq;
;                         const f32x4 xv = *(const f32x4*)(x + off);
;                         f32x4 o = acc[ai][bj][m][n];
;                         o.x += xv.x; o.y += xv.y; o.z += xv.z; o.w += xv.w;
;                         acc[ai][bj][m][n] = o;
;                         ss += (o.x * o.x + o.y * o.y) + (o.z * o.z + o.w * o.w);
;                     }
;                 ss = xor16_sum(ss); ss = xor32_sum(ss);
;                 if (fq == 0) ssqh[tok * 16 + u.pn * 4 + wc] = ss;
;             }
.LBB0_2002:
	s_lshl_b32 s14, s26, 5
	s_add_u32 s2, s70, 0xfe14f00
	s_mov_b32 s9, 0
	s_addc_u32 s3, s71, 0
	s_lshl_b64 s[0:1], s[8:9], 8
	s_ashr_i32 s4, s28, 31
	s_add_u32 s0, s0, s28
	s_addc_u32 s1, s1, s4
	v_or_b32_e32 v162, s0, v129
	s_lshl_b32 s0, s6, 2
	v_mov_b32_e32 v163, s1
	s_lshl_b32 s4, s6, 8
	s_ashr_i32 s1, s0, 31
	s_ashr_i32 s5, s4, 31
	s_lshl_b64 s[0:1], s[0:1], 2
	s_add_u32 s0, s2, s0
	v_readlane_b32 s36, v236, 1
	s_addc_u32 s1, s3, s1
	s_lshl_b32 s6, s26, 2
	v_lshlrev_b64 v[130:131], 12, v[162:163]
	v_readlane_b32 s37, v236, 2
	s_add_u32 s6, s0, s6
	s_addc_u32 s7, s1, 0
	v_lshl_add_u64 v[132:133], s[36:37], 0, v[130:131]
	v_lshl_add_u64 v[132:133], s[4:5], 2, v[132:133]
	s_lshl_b32 s0, s26, 7
	s_mov_b32 s1, s9
	v_mov_b32_e32 v129, 0
	v_lshl_add_u64 v[132:133], v[132:133], 0, s[0:1]
	v_lshl_add_u64 v[140:141], v[132:133], 0, v[128:129]
	s_barrier
	global_load_dwordx4 v[132:135], v[140:141], off
	global_load_dwordx4 v[136:139], v[140:141], off offset:64
	global_load_dwordx4 v[154:157], v[140:141], off offset:512
	global_load_dwordx4 v[158:161], v[140:141], off offset:576
	v_lshlrev_b32_e32 v164, 2, v142
	v_cmp_eq_u32_e32 vcc, 0, v142
	v_readlane_b32 s38, v236, 3
	v_readlane_b32 s39, v236, 4
	v_readlane_b32 s40, v236, 5
	v_readlane_b32 s41, v236, 6
	v_readlane_b32 s42, v236, 7
	v_readlane_b32 s43, v236, 8
	v_readlane_b32 s44, v236, 9
	v_readlane_b32 s45, v236, 10
	v_readlane_b32 s46, v236, 11
	v_readlane_b32 s47, v236, 12
	v_readlane_b32 s48, v236, 13
	v_readlane_b32 s49, v236, 14
	v_readlane_b32 s50, v236, 15
	v_readlane_b32 s51, v236, 16
	s_waitcnt vmcnt(0)
	v_pk_add_f32 v[150:151], v[126:127], v[134:135]
	v_pk_add_f32 v[152:153], v[124:125], v[132:133]
	v_pk_add_f32 v[146:147], v[122:123], v[138:139]
	v_pk_add_f32 v[148:149], v[120:121], v[136:137]
	v_pk_add_f32 v[140:141], v[118:119], v[156:157]
	v_pk_add_f32 v[142:143], v[116:117], v[154:155]
	v_pk_add_f32 v[136:137], v[114:115], v[160:161]
	v_pk_add_f32 v[138:139], v[112:113], v[158:159]
	v_mul_f32_e32 v112, v153, v153
	v_mul_f32_e32 v114, v151, v151
	v_mul_f32_e32 v116, v149, v149
	v_mul_f32_e32 v118, v147, v147
	v_mul_f32_e32 v120, v143, v143
	v_mul_f32_e32 v122, v141, v141
	v_pk_fma_f32 v[112:113], v[152:153], v[152:153], v[112:113] op_sel_hi:[1,1,0]
	v_pk_fma_f32 v[114:115], v[150:151], v[150:151], v[114:115] op_sel_hi:[1,1,0]
	v_pk_fma_f32 v[116:117], v[148:149], v[148:149], v[116:117] op_sel_hi:[1,1,0]
	v_pk_fma_f32 v[118:119], v[146:147], v[146:147], v[118:119] op_sel_hi:[1,1,0]
	v_mul_f32_e32 v124, v139, v139
	v_mul_f32_e32 v126, v137, v137
	v_pk_fma_f32 v[120:121], v[142:143], v[142:143], v[120:121] op_sel_hi:[1,1,0]
	v_pk_fma_f32 v[122:123], v[140:141], v[140:141], v[122:123] op_sel_hi:[1,1,0]
	v_pk_add_f32 v[112:113], v[112:113], v[114:115]
	v_pk_add_f32 v[114:115], v[116:117], v[118:119]
	v_pk_fma_f32 v[124:125], v[138:139], v[138:139], v[124:125] op_sel_hi:[1,1,0]
	v_pk_fma_f32 v[126:127], v[136:137], v[136:137], v[126:127] op_sel_hi:[1,1,0]
	v_pk_add_f32 v[116:117], v[120:121], v[122:123]
	v_pk_add_f32 v[112:113], v[112:113], v[114:115]
	v_pk_add_f32 v[118:119], v[124:125], v[126:127]
	v_pk_add_f32 v[112:113], v[112:113], v[116:117]
	v_lshlrev_b64 v[156:157], 6, v[162:163]
	v_pk_add_f32 v[112:113], v[112:113], v[118:119]
	s_nop 0
	v_mov_b32_e32 v113, v112
	s_nop 1
	v_permlane16_swap_b32_e32 v112, v113
	v_add_f32_e32 v112, v112, v113
	v_mov_b32_e32 v113, v112
	s_nop 1
	v_permlane32_swap_b32_e32 v112, v113
	s_and_saveexec_b64 s[10:11], vcc
	s_cbranch_execz .LBB0_2004
	v_add_f32_e32 v114, v112, v113
	v_lshl_add_u64 v[112:113], s[6:7], 0, v[156:157]
	global_store_dword v[112:113], v114, off sc0 sc1
.LBB0_2004:
	s_or_b64 exec, exec, s[10:11]
	v_or_b32_e32 v144, 16, v162
	v_mov_b32_e32 v145, v163
	v_readlane_b32 s16, v236, 1
	v_lshlrev_b64 v[112:113], 12, v[144:145]
	v_readlane_b32 s17, v236, 2
	s_lshl_b32 s10, s14, 2
	s_mov_b32 s11, s9
	v_lshl_add_u64 v[114:115], s[16:17], 0, v[112:113]
	v_lshl_add_u64 v[114:115], s[4:5], 2, v[114:115]
	v_lshl_add_u64 v[114:115], v[114:115], 0, s[10:11]
	v_lshlrev_b32_e32 v128, 2, v164
	v_lshl_add_u64 v[122:123], v[114:115], 0, v[128:129]
	global_load_dwordx4 v[114:117], v[122:123], off
	global_load_dwordx4 v[118:121], v[122:123], off offset:64
	global_load_dwordx4 v[158:161], v[122:123], off offset:512
	global_load_dwordx4 v[166:169], v[122:123], off offset:576
	v_readlane_b32 s18, v236, 3
	v_readlane_b32 s19, v236, 4
	v_readlane_b32 s20, v236, 5
	v_readlane_b32 s21, v236, 6
	v_readlane_b32 s22, v236, 7
	v_readlane_b32 s23, v236, 8
	v_readlane_b32 s24, v236, 9
	v_readlane_b32 s25, v236, 10
	v_readlane_b32 s26, v236, 11
	v_readlane_b32 s27, v236, 12
	v_readlane_b32 s28, v236, 13
	v_readlane_b32 s29, v236, 14
	v_readlane_b32 s30, v236, 15
	v_readlane_b32 s31, v236, 16
	s_waitcnt vmcnt(3)
	v_pk_add_f32 v[132:133], v[110:111], v[116:117]
	v_pk_add_f32 v[134:135], v[108:109], v[114:115]
	s_waitcnt vmcnt(2)
	v_pk_add_f32 v[124:125], v[106:107], v[120:121]
	v_pk_add_f32 v[126:127], v[104:105], v[118:119]
	s_waitcnt vmcnt(1)
	v_pk_add_f32 v[120:121], v[102:103], v[160:161]
	v_pk_add_f32 v[122:123], v[100:101], v[158:159]
	s_waitcnt vmcnt(0)
	v_pk_add_f32 v[114:115], v[98:99], v[168:169]
	v_pk_add_f32 v[116:117], v[96:97], v[166:167]
	v_mul_f32_e32 v96, v135, v135
	v_mul_f32_e32 v98, v133, v133
	v_mul_f32_e32 v100, v127, v127
	v_mul_f32_e32 v102, v125, v125
	v_mul_f32_e32 v104, v123, v123
	v_mul_f32_e32 v106, v121, v121
	v_pk_fma_f32 v[96:97], v[134:135], v[134:135], v[96:97] op_sel_hi:[1,1,0]
	v_pk_fma_f32 v[98:99], v[132:133], v[132:133], v[98:99] op_sel_hi:[1,1,0]
	v_pk_fma_f32 v[100:101], v[126:127], v[126:127], v[100:101] op_sel_hi:[1,1,0]
	v_pk_fma_f32 v[102:103], v[124:125], v[124:125], v[102:103] op_sel_hi:[1,1,0]
	v_mul_f32_e32 v108, v117, v117
	v_mul_f32_e32 v110, v115, v115
	v_pk_fma_f32 v[104:105], v[122:123], v[122:123], v[104:105] op_sel_hi:[1,1,0]
	v_pk_fma_f32 v[106:107], v[120:121], v[120:121], v[106:107] op_sel_hi:[1,1,0]
	v_pk_add_f32 v[96:97], v[96:97], v[98:99]
	v_pk_add_f32 v[98:99], v[100:101], v[102:103]
	v_pk_fma_f32 v[108:109], v[116:117], v[116:117], v[108:109] op_sel_hi:[1,1,0]
	v_pk_fma_f32 v[110:111], v[114:115], v[114:115], v[110:111] op_sel_hi:[1,1,0]
	v_pk_add_f32 v[100:101], v[104:105], v[106:107]
	v_pk_add_f32 v[96:97], v[96:97], v[98:99]
	v_pk_add_f32 v[102:103], v[108:109], v[110:111]
	v_pk_add_f32 v[96:97], v[96:97], v[100:101]
	v_lshlrev_b64 v[160:161], 6, v[144:145]
	v_pk_add_f32 v[96:97], v[96:97], v[102:103]
	s_nop 0
	v_mov_b32_e32 v97, v96
	s_nop 1
	v_permlane16_swap_b32_e32 v96, v97
	v_add_f32_e32 v96, v96, v97
	v_mov_b32_e32 v97, v96
	s_nop 1
	v_permlane32_swap_b32_e32 v96, v97
	s_and_saveexec_b64 s[12:13], vcc
	s_cbranch_execz .LBB0_2006
	v_add_f32_e32 v98, v96, v97
	v_lshl_add_u64 v[96:97], s[6:7], 0, v[160:161]
	global_store_dword v[96:97], v98, off sc0 sc1
; DI float xor32_sum(float x) { auto r = __builtin_amdgcn_permlane32_swap(__float_as_uint(x), __float_as_uint(x), false, false); return __uint_as_float(r[0]) + __uint_as_float(r[1]); }
; DI float xor16_sum(float x) { auto r = __builtin_amdgcn_permlane16_swap(__float_as_uint(x), __float_as_uint(x), false, false); return __uint_as_float(r[0]) + __uint_as_float(r[1]); }
;     DI void fused(pg8::f32x4 (&acc)[2][2][4][2], const pg8::Unit& u, int wr, int wc, int fr, int fq, PG8_LAS unsigned char* lds, int wid, int lane) const {
;     ...
; #pragma unroll
;         for (int ai = 0; ai < 2; ++ai)
; #pragma unroll
;             for (int m = 0; m < 4; ++m) {
;                 const size_t tok = (size_t)u.pm * 256 + ai * 128 + wr * 64 + m * 16 + fr;
;                 float ss = 0.f;
; #pragma unroll
;                 for (int bj = 0; bj < 2; ++bj)
; #pragma unroll
;                     for (int n = 0; n < 2; ++n) {
;                         const size_t off = tok * 1024 + u.pn * 256 + bj * 128 + wc * 32 + n * 16 + 4 * fq;
;                         const f32x4 xv = *(const f32x4*)(x + off);
;                         f32x4 o = acc[ai][bj][m][n];
;                         o.x += xv.x; o.y += xv.y; o.z += xv.z; o.w += xv.w;
;                         acc[ai][bj][m][n] = o;
;                         ss += (o.x * o.x + o.y * o.y) + (o.z * o.z + o.w * o.w);
;                     }
;                 ss = xor16_sum(ss); ss = xor32_sum(ss);
;                 if (fq == 0) ssqh[tok * 16 + u.pn * 4 + wc] = ss;
;             }
.LBB0_2006:
	s_or_b64 exec, exec, s[12:13]
	v_or_b32_e32 v118, 32, v162
	v_mov_b32_e32 v119, v163
	v_readlane_b32 s16, v236, 1
	v_lshlrev_b64 v[96:97], 12, v[118:119]
	v_readlane_b32 s17, v236, 2
	s_mov_b32 s11, 0
	v_mov_b32_e32 v129, 0
	v_lshl_add_u64 v[98:99], s[16:17], 0, v[96:97]
	v_lshl_add_u64 v[98:99], s[4:5], 2, v[98:99]
	v_lshl_add_u64 v[98:99], v[98:99], 0, s[10:11]
	v_lshl_add_u64 v[106:107], v[98:99], 0, v[128:129]
	global_load_dwordx4 v[98:101], v[106:107], off
	global_load_dwordx4 v[102:105], v[106:107], off offset:64
	global_load_dwordx4 v[166:169], v[106:107], off offset:512
	global_load_dwordx4 v[170:173], v[106:107], off offset:576
	v_lshlrev_b64 v[158:159], 6, v[118:119]
	v_readlane_b32 s18, v236, 3
	v_readlane_b32 s19, v236, 4
	v_readlane_b32 s20, v236, 5
	v_readlane_b32 s21, v236, 6
	v_readlane_b32 s22, v236, 7
	v_readlane_b32 s23, v236, 8
	v_readlane_b32 s24, v236, 9
	v_readlane_b32 s25, v236, 10
	v_readlane_b32 s26, v236, 11
	v_readlane_b32 s27, v236, 12
	v_readlane_b32 s28, v236, 13
	v_readlane_b32 s29, v236, 14
	v_readlane_b32 s30, v236, 15
	v_readlane_b32 s31, v236, 16
	s_waitcnt vmcnt(3)
	v_pk_add_f32 v[108:109], v[94:95], v[100:101]
	v_pk_add_f32 v[110:111], v[92:93], v[98:99]
	s_waitcnt vmcnt(2)
	v_pk_add_f32 v[104:105], v[90:91], v[104:105]
	v_pk_add_f32 v[106:107], v[88:89], v[102:103]
	s_waitcnt vmcnt(1)
	v_pk_add_f32 v[100:101], v[86:87], v[168:169]
	v_pk_add_f32 v[102:103], v[84:85], v[166:167]
	s_waitcnt vmcnt(0)
	v_pk_add_f32 v[92:93], v[82:83], v[172:173]
	v_pk_add_f32 v[94:95], v[80:81], v[170:171]
	v_mul_f32_e32 v80, v111, v111
	v_mul_f32_e32 v82, v109, v109
	v_mul_f32_e32 v84, v107, v107
	v_mul_f32_e32 v86, v105, v105
	v_mul_f32_e32 v88, v103, v103
	v_mul_f32_e32 v90, v101, v101
	v_pk_fma_f32 v[80:81], v[110:111], v[110:111], v[80:81] op_sel_hi:[1,1,0]
	v_pk_fma_f32 v[82:83], v[108:109], v[108:109], v[82:83] op_sel_hi:[1,1,0]
	v_pk_fma_f32 v[84:85], v[106:107], v[106:107], v[84:85] op_sel_hi:[1,1,0]
	v_pk_fma_f32 v[86:87], v[104:105], v[104:105], v[86:87] op_sel_hi:[1,1,0]
	v_mul_f32_e32 v98, v95, v95
	v_mul_f32_e32 v144, v93, v93
	v_pk_fma_f32 v[88:89], v[102:103], v[102:103], v[88:89] op_sel_hi:[1,1,0]
	v_pk_fma_f32 v[90:91], v[100:101], v[100:101], v[90:91] op_sel_hi:[1,1,0]
	v_pk_add_f32 v[80:81], v[80:81], v[82:83]
	v_pk_add_f32 v[82:83], v[84:85], v[86:87]
	v_pk_fma_f32 v[98:99], v[94:95], v[94:95], v[98:99] op_sel_hi:[1,1,0]
	v_pk_fma_f32 v[144:145], v[92:93], v[92:93], v[144:145] op_sel_hi:[1,1,0]
	v_pk_add_f32 v[84:85], v[88:89], v[90:91]
	v_pk_add_f32 v[80:81], v[80:81], v[82:83]
	v_pk_add_f32 v[86:87], v[98:99], v[144:145]
	v_pk_add_f32 v[80:81], v[80:81], v[84:85]
	s_nop 0
	v_pk_add_f32 v[80:81], v[80:81], v[86:87]
	s_nop 0
	v_mov_b32_e32 v81, v80
	s_nop 1
	v_permlane16_swap_b32_e32 v80, v81
	v_add_f32_e32 v80, v80, v81
	v_mov_b32_e32 v81, v80
	s_nop 1
	v_permlane32_swap_b32_e32 v80, v81
	s_and_saveexec_b64 s[12:13], vcc
	s_cbranch_execz .LBB0_2008
	v_add_f32_e32 v82, v80, v81
	v_lshl_add_u64 v[80:81], s[6:7], 0, v[158:159]
	global_store_dword v[80:81], v82, off sc0 sc1
.LBB0_2008:
	s_or_b64 exec, exec, s[12:13]
	v_or_b32_e32 v98, 48, v162
	v_mov_b32_e32 v99, v163
	v_readlane_b32 s16, v236, 1
	v_lshlrev_b64 v[80:81], 12, v[98:99]
	v_readlane_b32 s17, v236, 2
	v_readlane_b32 s18, v236, 3
	v_readlane_b32 s19, v236, 4
	v_lshl_add_u64 v[82:83], s[16:17], 0, v[80:81]
	v_lshl_add_u64 v[82:83], s[4:5], 2, v[82:83]
	v_lshl_add_u64 v[82:83], v[82:83], 0, s[10:11]
	v_lshl_add_u64 v[86:87], v[82:83], 0, v[128:129]
	global_load_dwordx4 v[82:85], v[86:87], off
	global_load_dwordx4 v[166:169], v[86:87], off offset:64
	global_load_dwordx4 v[170:173], v[86:87], off offset:512
	global_load_dwordx4 v[174:177], v[86:87], off offset:576
	v_readlane_b32 s20, v236, 5
	v_readlane_b32 s21, v236, 6
	v_readlane_b32 s22, v236, 7
	v_readlane_b32 s23, v236, 8
	v_readlane_b32 s24, v236, 9
	v_readlane_b32 s25, v236, 10
	v_readlane_b32 s26, v236, 11
	v_readlane_b32 s27, v236, 12
	v_readlane_b32 s28, v236, 13
	v_readlane_b32 s29, v236, 14
	v_readlane_b32 s30, v236, 15
	v_readlane_b32 s31, v236, 16
	s_waitcnt vmcnt(3)
	v_pk_add_f32 v[88:89], v[78:79], v[84:85]
	v_pk_add_f32 v[90:91], v[76:77], v[82:83]
	s_waitcnt vmcnt(2)
	v_pk_add_f32 v[84:85], v[74:75], v[168:169]
	v_pk_add_f32 v[86:87], v[72:73], v[166:167]
	s_waitcnt vmcnt(1)
	v_pk_add_f32 v[78:79], v[70:71], v[172:173]
	v_pk_add_f32 v[82:83], v[68:69], v[170:171]
	s_waitcnt vmcnt(0)
	v_pk_add_f32 v[72:73], v[66:67], v[176:177]
	v_pk_add_f32 v[74:75], v[64:65], v[174:175]
	v_mul_f32_e32 v64, v91, v91
	v_mul_f32_e32 v66, v89, v89
	v_mul_f32_e32 v68, v87, v87
	v_mul_f32_e32 v70, v85, v85
	v_mul_f32_e32 v76, v83, v83
	v_mul_f32_e32 v118, v79, v79
	v_pk_fma_f32 v[64:65], v[90:91], v[90:91], v[64:65] op_sel_hi:[1,1,0]
	v_pk_fma_f32 v[66:67], v[88:89], v[88:89], v[66:67] op_sel_hi:[1,1,0]
	v_pk_fma_f32 v[68:69], v[86:87], v[86:87], v[68:69] op_sel_hi:[1,1,0]
	v_pk_fma_f32 v[70:71], v[84:85], v[84:85], v[70:71] op_sel_hi:[1,1,0]
	v_mul_f32_e32 v144, v75, v75
	v_mul_f32_e32 v154, v73, v73
	v_pk_fma_f32 v[76:77], v[82:83], v[82:83], v[76:77] op_sel_hi:[1,1,0]
	v_pk_fma_f32 v[118:119], v[78:79], v[78:79], v[118:119] op_sel_hi:[1,1,0]
	v_pk_add_f32 v[64:65], v[64:65], v[66:67]
	v_pk_add_f32 v[66:67], v[68:69], v[70:71]
	v_pk_fma_f32 v[144:145], v[74:75], v[74:75], v[144:145] op_sel_hi:[1,1,0]
	v_pk_fma_f32 v[154:155], v[72:73], v[72:73], v[154:155] op_sel_hi:[1,1,0]
	v_pk_add_f32 v[68:69], v[76:77], v[118:119]
	v_pk_add_f32 v[64:65], v[64:65], v[66:67]
	v_pk_add_f32 v[70:71], v[144:145], v[154:155]
	v_pk_add_f32 v[64:65], v[64:65], v[68:69]
	v_lshlrev_b64 v[154:155], 6, v[98:99]
	v_pk_add_f32 v[64:65], v[64:65], v[70:71]
	s_nop 0
	v_mov_b32_e32 v65, v64
	s_nop 1
	v_permlane16_swap_b32_e32 v64, v65
	v_add_f32_e32 v64, v64, v65
	v_mov_b32_e32 v65, v64
	s_nop 1
	v_permlane32_swap_b32_e32 v64, v65
	s_and_saveexec_b64 s[12:13], vcc
	s_cbranch_execz .LBB0_2010
	v_add_f32_e32 v66, v64, v65
	v_lshl_add_u64 v[64:65], s[6:7], 0, v[154:155]
	global_store_dword v[64:65], v66, off sc0 sc1
; DI float xor32_sum(float x) { auto r = __builtin_amdgcn_permlane32_swap(__float_as_uint(x), __float_as_uint(x), false, false); return __uint_as_float(r[0]) + __uint_as_float(r[1]); }
; DI float xor16_sum(float x) { auto r = __builtin_amdgcn_permlane16_swap(__float_as_uint(x), __float_as_uint(x), false, false); return __uint_as_float(r[0]) + __uint_as_float(r[1]); }
;     DI void fused(pg8::f32x4 (&acc)[2][2][4][2], const pg8::Unit& u, int wr, int wc, int fr, int fq, PG8_LAS unsigned char* lds, int wid, int lane) const {
;     ...
; #pragma unroll
;         for (int ai = 0; ai < 2; ++ai)
; #pragma unroll
;             for (int m = 0; m < 4; ++m) {
;                 const size_t tok = (size_t)u.pm * 256 + ai * 128 + wr * 64 + m * 16 + fr;
;                 float ss = 0.f;
; #pragma unroll
;                 for (int bj = 0; bj < 2; ++bj)
; #pragma unroll
;                     for (int n = 0; n < 2; ++n) {
;                         const size_t off = tok * 1024 + u.pn * 256 + bj * 128 + wc * 32 + n * 16 + 4 * fq;
;                         const f32x4 xv = *(const f32x4*)(x + off);
;                         f32x4 o = acc[ai][bj][m][n];
;                         o.x += xv.x; o.y += xv.y; o.z += xv.z; o.w += xv.w;
;                         acc[ai][bj][m][n] = o;
;                         ss += (o.x * o.x + o.y * o.y) + (o.z * o.z + o.w * o.w);
;                     }
;                 ss = xor16_sum(ss); ss = xor32_sum(ss);
;                 if (fq == 0) ssqh[tok * 16 + u.pn * 4 + wc] = ss;
;             }
.LBB0_2010:
	s_or_b64 exec, exec, s[12:13]
	s_mov_b64 s[0:1], 0x80
	v_lshl_add_u64 v[76:77], v[162:163], 0, s[0:1]
	v_readlane_b32 s16, v236, 1
	v_lshlrev_b64 v[64:65], 12, v[76:77]
	v_readlane_b32 s17, v236, 2
	v_mov_b32_e32 v129, 0
	v_readlane_b32 s18, v236, 3
	v_lshl_add_u64 v[66:67], s[16:17], 0, v[64:65]
	v_lshl_add_u64 v[66:67], s[4:5], 2, v[66:67]
	v_lshl_add_u64 v[66:67], v[66:67], 0, s[10:11]
	v_lshl_add_u64 v[70:71], v[66:67], 0, v[128:129]
	global_load_dwordx4 v[66:69], v[70:71], off
	global_load_dwordx4 v[166:169], v[70:71], off offset:64
	global_load_dwordx4 v[170:173], v[70:71], off offset:512
	global_load_dwordx4 v[174:177], v[70:71], off offset:576
	v_readlane_b32 s19, v236, 4
	v_readlane_b32 s20, v236, 5
	v_readlane_b32 s21, v236, 6
	v_readlane_b32 s22, v236, 7
	v_readlane_b32 s23, v236, 8
	v_readlane_b32 s24, v236, 9
	v_readlane_b32 s25, v236, 10
	v_readlane_b32 s26, v236, 11
	v_readlane_b32 s27, v236, 12
	v_readlane_b32 s28, v236, 13
	v_readlane_b32 s29, v236, 14
	v_readlane_b32 s30, v236, 15
	v_readlane_b32 s31, v236, 16
	s_waitcnt vmcnt(3)
	v_pk_add_f32 v[68:69], v[62:63], v[68:69]
	v_pk_add_f32 v[70:71], v[60:61], v[66:67]
	s_waitcnt vmcnt(2)
	v_pk_add_f32 v[62:63], v[58:59], v[168:169]
	v_pk_add_f32 v[66:67], v[56:57], v[166:167]
	s_waitcnt vmcnt(1)
	v_pk_add_f32 v[58:59], v[54:55], v[172:173]
	v_pk_add_f32 v[60:61], v[52:53], v[170:171]
	s_waitcnt vmcnt(0)
	v_pk_add_f32 v[54:55], v[50:51], v[176:177]
	v_pk_add_f32 v[56:57], v[48:49], v[174:175]
	v_mul_f32_e32 v48, v71, v71
	v_mul_f32_e32 v50, v69, v69
	v_mul_f32_e32 v52, v67, v67
	v_mul_f32_e32 v98, v63, v63
	v_mul_f32_e32 v118, v61, v61
	v_mul_f32_e32 v144, v59, v59
	v_pk_fma_f32 v[48:49], v[70:71], v[70:71], v[48:49] op_sel_hi:[1,1,0]
	v_pk_fma_f32 v[50:51], v[68:69], v[68:69], v[50:51] op_sel_hi:[1,1,0]
	v_pk_fma_f32 v[52:53], v[66:67], v[66:67], v[52:53] op_sel_hi:[1,1,0]
	v_pk_fma_f32 v[98:99], v[62:63], v[62:63], v[98:99] op_sel_hi:[1,1,0]
	v_mul_f32_e32 v166, v57, v57
	v_mul_f32_e32 v168, v55, v55
	v_pk_fma_f32 v[118:119], v[60:61], v[60:61], v[118:119] op_sel_hi:[1,1,0]
	v_pk_fma_f32 v[144:145], v[58:59], v[58:59], v[144:145] op_sel_hi:[1,1,0]
	v_pk_add_f32 v[48:49], v[48:49], v[50:51]
	v_pk_add_f32 v[50:51], v[52:53], v[98:99]
	v_pk_fma_f32 v[166:167], v[56:57], v[56:57], v[166:167] op_sel_hi:[1,1,0]
	v_pk_fma_f32 v[168:169], v[54:55], v[54:55], v[168:169] op_sel_hi:[1,1,0]
	v_pk_add_f32 v[52:53], v[118:119], v[144:145]
	v_pk_add_f32 v[48:49], v[48:49], v[50:51]
	v_pk_add_f32 v[98:99], v[166:167], v[168:169]
	v_pk_add_f32 v[48:49], v[48:49], v[52:53]
	v_lshlrev_b64 v[144:145], 6, v[76:77]
	v_pk_add_f32 v[48:49], v[48:49], v[98:99]
	s_nop 0
	v_mov_b32_e32 v49, v48
	s_nop 1
	v_permlane16_swap_b32_e32 v48, v49
	v_add_f32_e32 v48, v48, v49
	v_mov_b32_e32 v49, v48
	s_nop 1
	v_permlane32_swap_b32_e32 v48, v49
	s_and_saveexec_b64 s[12:13], vcc
	s_cbranch_execz .LBB0_2012
	v_add_f32_e32 v50, v48, v49
	v_lshl_add_u64 v[48:49], s[6:7], 0, v[144:145]
	global_store_dword v[48:49], v50, off sc0 sc1
.LBB0_2012:
	s_or_b64 exec, exec, s[12:13]
	s_mov_b64 s[0:1], 0x90
	v_lshl_add_u64 v[76:77], v[162:163], 0, s[0:1]
	v_readlane_b32 s16, v236, 1
	v_lshlrev_b64 v[48:49], 12, v[76:77]
	v_readlane_b32 s17, v236, 2
	v_readlane_b32 s18, v236, 3
	v_readlane_b32 s19, v236, 4
	v_lshl_add_u64 v[50:51], s[16:17], 0, v[48:49]
	v_lshl_add_u64 v[50:51], s[4:5], 2, v[50:51]
	v_lshl_add_u64 v[50:51], v[50:51], 0, s[10:11]
	v_lshl_add_u64 v[50:51], v[50:51], 0, v[128:129]
	global_load_dwordx4 v[166:169], v[50:51], off
	global_load_dwordx4 v[170:173], v[50:51], off offset:64
	global_load_dwordx4 v[174:177], v[50:51], off offset:512
	global_load_dwordx4 v[178:181], v[50:51], off offset:576
	v_readlane_b32 s20, v236, 5
	v_readlane_b32 s21, v236, 6
	v_readlane_b32 s22, v236, 7
	v_readlane_b32 s23, v236, 8
	v_readlane_b32 s24, v236, 9
	v_readlane_b32 s25, v236, 10
	v_readlane_b32 s26, v236, 11
	v_readlane_b32 s27, v236, 12
	v_readlane_b32 s28, v236, 13
	v_readlane_b32 s29, v236, 14
	v_readlane_b32 s30, v236, 15
	v_readlane_b32 s31, v236, 16
	s_waitcnt vmcnt(3)
	v_pk_add_f32 v[50:51], v[46:47], v[168:169]
	v_pk_add_f32 v[52:53], v[44:45], v[166:167]
	s_waitcnt vmcnt(2)
	v_pk_add_f32 v[44:45], v[42:43], v[172:173]
	v_pk_add_f32 v[46:47], v[40:41], v[170:171]
	s_waitcnt vmcnt(1)
	v_pk_add_f32 v[40:41], v[38:39], v[176:177]
	v_pk_add_f32 v[42:43], v[36:37], v[174:175]
	s_waitcnt vmcnt(0)
	v_pk_add_f32 v[36:37], v[34:35], v[180:181]
	v_pk_add_f32 v[38:39], v[32:33], v[178:179]
	v_mul_f32_e32 v32, v53, v53
	v_mul_f32_e32 v34, v51, v51
	v_mul_f32_e32 v98, v47, v47
	v_mul_f32_e32 v118, v45, v45
	v_mul_f32_e32 v166, v43, v43
	v_mul_f32_e32 v168, v41, v41
	v_pk_fma_f32 v[32:33], v[52:53], v[52:53], v[32:33] op_sel_hi:[1,1,0]
	v_pk_fma_f32 v[34:35], v[50:51], v[50:51], v[34:35] op_sel_hi:[1,1,0]
	v_pk_fma_f32 v[98:99], v[46:47], v[46:47], v[98:99] op_sel_hi:[1,1,0]
	v_pk_fma_f32 v[118:119], v[44:45], v[44:45], v[118:119] op_sel_hi:[1,1,0]
	v_mul_f32_e32 v170, v39, v39
	v_mul_f32_e32 v172, v37, v37
	v_pk_fma_f32 v[166:167], v[42:43], v[42:43], v[166:167] op_sel_hi:[1,1,0]
	v_pk_fma_f32 v[168:169], v[40:41], v[40:41], v[168:169] op_sel_hi:[1,1,0]
	v_pk_add_f32 v[32:33], v[32:33], v[34:35]
	v_pk_add_f32 v[34:35], v[98:99], v[118:119]
	v_pk_fma_f32 v[170:171], v[38:39], v[38:39], v[170:171] op_sel_hi:[1,1,0]
	v_pk_fma_f32 v[172:173], v[36:37], v[36:37], v[172:173] op_sel_hi:[1,1,0]
	v_pk_add_f32 v[98:99], v[166:167], v[168:169]
	v_pk_add_f32 v[32:33], v[32:33], v[34:35]
	v_pk_add_f32 v[118:119], v[170:171], v[172:173]
	v_pk_add_f32 v[32:33], v[32:33], v[98:99]
	s_nop 0
	v_pk_add_f32 v[32:33], v[32:33], v[118:119]
	v_lshlrev_b64 v[118:119], 6, v[76:77]
	v_mov_b32_e32 v33, v32
	s_nop 1
	v_permlane16_swap_b32_e32 v32, v33
	v_add_f32_e32 v32, v32, v33
	v_mov_b32_e32 v33, v32
	s_nop 1
	v_permlane32_swap_b32_e32 v32, v33
	s_and_saveexec_b64 s[12:13], vcc
	s_cbranch_execz .LBB0_2014
	v_add_f32_e32 v34, v32, v33
	v_lshl_add_u64 v[32:33], s[6:7], 0, v[118:119]
	global_store_dword v[32:33], v34, off sc0 sc1
; DI float xor32_sum(float x) { auto r = __builtin_amdgcn_permlane32_swap(__float_as_uint(x), __float_as_uint(x), false, false); return __uint_as_float(r[0]) + __uint_as_float(r[1]); }
; DI float xor16_sum(float x) { auto r = __builtin_amdgcn_permlane16_swap(__float_as_uint(x), __float_as_uint(x), false, false); return __uint_as_float(r[0]) + __uint_as_float(r[1]); }
;     DI void fused(pg8::f32x4 (&acc)[2][2][4][2], const pg8::Unit& u, int wr, int wc, int fr, int fq, PG8_LAS unsigned char* lds, int wid, int lane) const {
;     ...
; #pragma unroll
;         for (int ai = 0; ai < 2; ++ai)
; #pragma unroll
;             for (int m = 0; m < 4; ++m) {
;                 const size_t tok = (size_t)u.pm * 256 + ai * 128 + wr * 64 + m * 16 + fr;
;                 float ss = 0.f;
; #pragma unroll
;                 for (int bj = 0; bj < 2; ++bj)
; #pragma unroll
;                     for (int n = 0; n < 2; ++n) {
;                         const size_t off = tok * 1024 + u.pn * 256 + bj * 128 + wc * 32 + n * 16 + 4 * fq;
;                         const f32x4 xv = *(const f32x4*)(x + off);
;                         f32x4 o = acc[ai][bj][m][n];
;                         o.x += xv.x; o.y += xv.y; o.z += xv.z; o.w += xv.w;
;                         acc[ai][bj][m][n] = o;
;                         ss += (o.x * o.x + o.y * o.y) + (o.z * o.z + o.w * o.w);
;                     }
;                 ss = xor16_sum(ss); ss = xor32_sum(ss);
;                 if (fq == 0) ssqh[tok * 16 + u.pn * 4 + wc] = ss;
;             }
;         asm volatile("s_waitcnt vmcnt(0)" ::: "memory");
;         __syncthreads();
;         if (threadIdx.x == 0) {
;             __builtin_amdgcn_fence(__ATOMIC_RELEASE, "agent");
;             asm volatile("s_waitcnt vmcnt(0)" ::: "memory");
;             __hip_atomic_fetch_add(pcnt, 1u, __ATOMIC_RELAXED, __HIP_MEMORY_SCOPE_AGENT);
.LBB0_2014:
	s_or_b64 exec, exec, s[12:13]
	s_mov_b64 s[0:1], 0xa0
	v_lshl_add_u64 v[76:77], v[162:163], 0, s[0:1]
	v_readlane_b32 s16, v236, 1
	v_lshlrev_b64 v[32:33], 12, v[76:77]
	v_readlane_b32 s17, v236, 2
	v_mov_b32_e32 v129, 0
	v_readlane_b32 s18, v236, 3
	v_lshl_add_u64 v[34:35], s[16:17], 0, v[32:33]
	v_lshl_add_u64 v[34:35], s[4:5], 2, v[34:35]
	v_lshl_add_u64 v[34:35], v[34:35], 0, s[10:11]
	v_lshl_add_u64 v[34:35], v[34:35], 0, v[128:129]
	global_load_dwordx4 v[166:169], v[34:35], off
	global_load_dwordx4 v[170:173], v[34:35], off offset:64
	global_load_dwordx4 v[174:177], v[34:35], off offset:512
	global_load_dwordx4 v[178:181], v[34:35], off offset:576
	v_readlane_b32 s19, v236, 4
	v_readlane_b32 s20, v236, 5
	v_readlane_b32 s21, v236, 6
	v_readlane_b32 s22, v236, 7
	v_readlane_b32 s23, v236, 8
	v_readlane_b32 s24, v236, 9
	v_readlane_b32 s25, v236, 10
	v_readlane_b32 s26, v236, 11
	v_readlane_b32 s27, v236, 12
	v_readlane_b32 s28, v236, 13
	v_readlane_b32 s29, v236, 14
	v_readlane_b32 s30, v236, 15
	v_readlane_b32 s31, v236, 16
	s_waitcnt vmcnt(3)
	v_pk_add_f32 v[30:31], v[30:31], v[168:169]
	v_pk_add_f32 v[34:35], v[28:29], v[166:167]
	s_waitcnt vmcnt(2)
	v_pk_add_f32 v[26:27], v[26:27], v[172:173]
	v_pk_add_f32 v[28:29], v[24:25], v[170:171]
	s_waitcnt vmcnt(1)
	v_pk_add_f32 v[22:23], v[22:23], v[176:177]
	v_pk_add_f32 v[24:25], v[20:21], v[174:175]
	s_waitcnt vmcnt(0)
	v_pk_add_f32 v[20:21], v[16:17], v[178:179]
	v_mul_f32_e32 v16, v35, v35
	v_mul_f32_e32 v98, v31, v31
	v_mul_f32_e32 v166, v29, v29
	v_mul_f32_e32 v168, v27, v27
	v_pk_add_f32 v[18:19], v[18:19], v[180:181]
	v_mul_f32_e32 v170, v25, v25
	v_mul_f32_e32 v172, v23, v23
	v_pk_fma_f32 v[16:17], v[34:35], v[34:35], v[16:17] op_sel_hi:[1,1,0]
	v_pk_fma_f32 v[98:99], v[30:31], v[30:31], v[98:99] op_sel_hi:[1,1,0]
	v_pk_fma_f32 v[166:167], v[28:29], v[28:29], v[166:167] op_sel_hi:[1,1,0]
	v_pk_fma_f32 v[168:169], v[26:27], v[26:27], v[168:169] op_sel_hi:[1,1,0]
	v_mul_f32_e32 v174, v21, v21
	v_mul_f32_e32 v176, v19, v19
	v_pk_fma_f32 v[170:171], v[24:25], v[24:25], v[170:171] op_sel_hi:[1,1,0]
	v_pk_fma_f32 v[172:173], v[22:23], v[22:23], v[172:173] op_sel_hi:[1,1,0]
	v_pk_add_f32 v[16:17], v[16:17], v[98:99]
	v_pk_add_f32 v[98:99], v[166:167], v[168:169]
	v_pk_fma_f32 v[174:175], v[20:21], v[20:21], v[174:175] op_sel_hi:[1,1,0]
	v_pk_fma_f32 v[176:177], v[18:19], v[18:19], v[176:177] op_sel_hi:[1,1,0]
	v_pk_add_f32 v[166:167], v[170:171], v[172:173]
	v_pk_add_f32 v[16:17], v[16:17], v[98:99]
	v_pk_add_f32 v[168:169], v[174:175], v[176:177]
	v_pk_add_f32 v[16:17], v[16:17], v[166:167]
	v_lshlrev_b64 v[98:99], 6, v[76:77]
	v_pk_add_f32 v[16:17], v[16:17], v[168:169]
	s_nop 0
	v_mov_b32_e32 v17, v16
	s_nop 1
	v_permlane16_swap_b32_e32 v16, v17
	v_add_f32_e32 v16, v16, v17
	v_mov_b32_e32 v17, v16
	s_nop 1
	v_permlane32_swap_b32_e32 v16, v17
	s_and_saveexec_b64 s[12:13], vcc
	s_cbranch_execz .LBB0_2016
	v_add_f32_e32 v76, v16, v17
	v_lshl_add_u64 v[16:17], s[6:7], 0, v[98:99]
	global_store_dword v[16:17], v76, off sc0 sc1
.LBB0_2016:
	s_or_b64 exec, exec, s[12:13]
	s_mov_b64 s[0:1], 0xb0
	v_lshl_add_u64 v[76:77], v[162:163], 0, s[0:1]
	v_readlane_b32 s16, v236, 1
	v_lshlrev_b64 v[16:17], 12, v[76:77]
	v_readlane_b32 s17, v236, 2
	v_lshlrev_b64 v[76:77], 6, v[76:77]
	v_readlane_b32 s18, v236, 3
	v_lshl_add_u64 v[162:163], s[16:17], 0, v[16:17]
	v_lshl_add_u64 v[162:163], s[4:5], 2, v[162:163]
	v_lshl_add_u64 v[162:163], v[162:163], 0, s[10:11]
	v_lshl_add_u64 v[128:129], v[162:163], 0, v[128:129]
	global_load_dwordx4 v[166:169], v[128:129], off
	global_load_dwordx4 v[170:173], v[128:129], off offset:64
	global_load_dwordx4 v[174:177], v[128:129], off offset:512
	global_load_dwordx4 v[178:181], v[128:129], off offset:576
	v_readlane_b32 s19, v236, 4
	v_readlane_b32 s20, v236, 5
	v_readlane_b32 s21, v236, 6
	v_readlane_b32 s22, v236, 7
	v_readlane_b32 s23, v236, 8
	v_readlane_b32 s24, v236, 9
	v_readlane_b32 s25, v236, 10
	v_readlane_b32 s26, v236, 11
	v_readlane_b32 s27, v236, 12
	v_readlane_b32 s28, v236, 13
	v_readlane_b32 s29, v236, 14
	v_readlane_b32 s30, v236, 15
	v_readlane_b32 s31, v236, 16
	s_waitcnt vmcnt(3)
	v_pk_add_f32 v[14:15], v[14:15], v[168:169]
	v_pk_add_f32 v[12:13], v[12:13], v[166:167]
	s_waitcnt vmcnt(2)
	v_pk_add_f32 v[10:11], v[10:11], v[172:173]
	v_pk_add_f32 v[8:9], v[8:9], v[170:171]
	s_waitcnt vmcnt(1)
	v_pk_add_f32 v[6:7], v[6:7], v[176:177]
	v_pk_add_f32 v[4:5], v[4:5], v[174:175]
	v_mul_f32_e32 v128, v13, v13
	v_mul_f32_e32 v162, v15, v15
	v_mul_f32_e32 v166, v9, v9
	v_mul_f32_e32 v168, v11, v11
	s_waitcnt vmcnt(0)
	v_pk_add_f32 v[2:3], v[2:3], v[180:181]
	v_pk_add_f32 v[0:1], v[0:1], v[178:179]
	v_mul_f32_e32 v170, v5, v5
	v_mul_f32_e32 v172, v7, v7
	v_pk_fma_f32 v[128:129], v[12:13], v[12:13], v[128:129] op_sel_hi:[1,1,0]
	v_pk_fma_f32 v[162:163], v[14:15], v[14:15], v[162:163] op_sel_hi:[1,1,0]
	v_pk_fma_f32 v[166:167], v[8:9], v[8:9], v[166:167] op_sel_hi:[1,1,0]
	v_pk_fma_f32 v[168:169], v[10:11], v[10:11], v[168:169] op_sel_hi:[1,1,0]
	v_mul_f32_e32 v174, v1, v1
	v_mul_f32_e32 v176, v3, v3
	v_pk_fma_f32 v[170:171], v[4:5], v[4:5], v[170:171] op_sel_hi:[1,1,0]
	v_pk_fma_f32 v[172:173], v[6:7], v[6:7], v[172:173] op_sel_hi:[1,1,0]
	v_pk_add_f32 v[128:129], v[128:129], v[162:163]
	v_pk_add_f32 v[162:163], v[166:167], v[168:169]
	v_pk_fma_f32 v[174:175], v[0:1], v[0:1], v[174:175] op_sel_hi:[1,1,0]
	v_pk_fma_f32 v[176:177], v[2:3], v[2:3], v[176:177] op_sel_hi:[1,1,0]
	v_pk_add_f32 v[166:167], v[170:171], v[172:173]
	v_pk_add_f32 v[128:129], v[128:129], v[162:163]
	v_pk_add_f32 v[168:169], v[174:175], v[176:177]
	v_pk_add_f32 v[128:129], v[128:129], v[166:167]
	s_nop 0
	v_pk_add_f32 v[128:129], v[128:129], v[168:169]
	s_nop 0
	v_mov_b32_e32 v129, v128
	s_nop 1
	v_permlane16_swap_b32_e32 v128, v129
	v_add_f32_e32 v128, v128, v129
	v_mov_b32_e32 v129, v128
	s_nop 1
	v_permlane32_swap_b32_e32 v128, v129
	s_and_saveexec_b64 s[10:11], vcc
	s_cbranch_execz .LBB0_2018
	v_add_f32_e32 v162, v128, v129
	v_lshl_add_u64 v[128:129], s[6:7], 0, v[76:77]
	global_store_dword v[128:129], v162, off sc0 sc1
.LBB0_2018:
	s_or_b64 exec, exec, s[10:11]
	s_waitcnt vmcnt(0)
	s_barrier
	s_mov_b64 s[6:7], exec
	v_readlane_b32 s0, v236, 33
	v_readlane_b32 s1, v236, 34
	s_and_b64 s[0:1], s[6:7], s[0:1]
	s_mov_b64 exec, s[0:1]
	s_cbranch_execz .LBB0_2033
	s_lshl_b64 s[0:1], s[8:9], 2
	s_mov_b64 s[10:11], exec
	s_add_u32 s0, s70, s0
	s_addc_u32 s1, s71, s1
	s_waitcnt vmcnt(0)
	s_waitcnt vmcnt(0)
	v_mbcnt_lo_u32_b32 v128, s10, 0
	s_add_u32 s0, s0, 0xff20800
	v_mbcnt_hi_u32_b32 v128, s11, v128
	s_addc_u32 s1, s1, 0
	v_cmp_eq_u32_e32 vcc, 0, v128
	s_and_saveexec_b64 s[8:9], vcc
	s_cbranch_execz .LBB0_2021
	s_bcnt1_i32_b64 s5, s[10:11]
	v_mov_b32_e32 v128, 0
	v_mov_b32_e32 v129, s5
	global_atomic_add v128, v129, s[0:1]
